# v112 with the context-path pad after the last QK MFMA restored to 12 wait states (s_nop 11): hazard-rule compliance, same schedule otherwise
# speedup vs baseline: 1.0099x; 1.0099x over previous
.LBB0_542:
	s_nop 11
